# indexer: per-wave tile-half max/min reduction by DPP row_ror + row_bcast:15 instead of five ds_bpermute stages
# speedup vs baseline: 1.0068x; 1.0057x over previous
; __device__ __forceinline__ void indexer_phase(const bf16_t* PJ, float* rk, unsigned short* SEL, LAS unsigned char* lds) {
;     ...
; #pragma unroll
;             for (int rt = 0; rt < 2; ++rt)
; #pragma unroll
;                 for (int qq = 0; qq < 2; ++qq) {
; #pragma unroll
;                     for (int o = 1; o < 32; o <<= 1) { rmax[rt][qq] = fmaxf(rmax[rt][qq], __shfl_xor(rmax[rt][qq], o)); rmin[rt][qq] = fminf(rmin[rt][qq], __shfl_xor(rmin[rt][qq], o)); }
;                     if (r32 == 0) { pmm[(wid * 8 + 4 * rt + 2 * hi + qq) * 2] = rmax[rt][qq]; pmm[(wid * 8 + 4 * rt + 2 * hi + qq) * 2 + 1] = rmin[rt][qq]; } }
.LBB0_874:
	s_waitcnt lgkmcnt(0)
	v_and_b32_e32 v11, 64, v180
	v_add_u32_e32 v0, 64, v11
	v_xor_b32_e32 v4, 1, v180
	v_cmp_lt_i32_e32 vcc, v4, v0
	s_nop 1
	v_cndmask_b32_e32 v4, v180, v4, vcc
	v_lshlrev_b32_e32 v20, 2, v4
	v_xor_b32_e32 v4, 2, v180
	v_cmp_lt_i32_e32 vcc, v4, v0
	s_nop 1
	v_cndmask_b32_e32 v4, v180, v4, vcc
	v_lshlrev_b32_e32 v21, 2, v4
	v_xor_b32_e32 v4, 4, v180
	v_cmp_lt_i32_e32 vcc, v4, v0
	s_nop 1
	v_cndmask_b32_e32 v4, v180, v4, vcc
	v_lshlrev_b32_e32 v22, 2, v4
	v_xor_b32_e32 v4, 8, v180
	v_cmp_lt_i32_e32 vcc, v4, v0
	s_nop 1
	v_cndmask_b32_e32 v4, v180, v4, vcc
	v_lshlrev_b32_e32 v23, 2, v4
	v_xor_b32_e32 v4, 16, v180
	v_cmp_lt_i32_e32 vcc, v4, v0
	s_nop 1
	v_cndmask_b32_e32 v4, v180, v4, vcc
	v_lshlrev_b32_e32 v24, 2, v4
	v_max_f32_dpp v189, v189, v189 row_ror:8 row_mask:0xf bank_mask:0xf
	v_min_f32_dpp v188, v188, v188 row_ror:8 row_mask:0xf bank_mask:0xf
	v_max_f32_dpp v187, v187, v187 row_ror:8 row_mask:0xf bank_mask:0xf
	v_min_f32_dpp v186, v186, v186 row_ror:8 row_mask:0xf bank_mask:0xf
	v_max_f32_dpp v185, v185, v185 row_ror:8 row_mask:0xf bank_mask:0xf
	v_min_f32_dpp v184, v184, v184 row_ror:8 row_mask:0xf bank_mask:0xf
	v_max_f32_dpp v183, v183, v183 row_ror:8 row_mask:0xf bank_mask:0xf
	v_min_f32_dpp v123, v123, v123 row_ror:8 row_mask:0xf bank_mask:0xf
	v_max_f32_dpp v189, v189, v189 row_ror:4 row_mask:0xf bank_mask:0xf
	v_min_f32_dpp v188, v188, v188 row_ror:4 row_mask:0xf bank_mask:0xf
	v_max_f32_dpp v187, v187, v187 row_ror:4 row_mask:0xf bank_mask:0xf
	v_min_f32_dpp v186, v186, v186 row_ror:4 row_mask:0xf bank_mask:0xf
	v_max_f32_dpp v185, v185, v185 row_ror:4 row_mask:0xf bank_mask:0xf
	v_min_f32_dpp v184, v184, v184 row_ror:4 row_mask:0xf bank_mask:0xf
	v_max_f32_dpp v183, v183, v183 row_ror:4 row_mask:0xf bank_mask:0xf
	v_min_f32_dpp v123, v123, v123 row_ror:4 row_mask:0xf bank_mask:0xf
	v_max_f32_dpp v189, v189, v189 row_ror:2 row_mask:0xf bank_mask:0xf
	v_min_f32_dpp v188, v188, v188 row_ror:2 row_mask:0xf bank_mask:0xf
	v_max_f32_dpp v187, v187, v187 row_ror:2 row_mask:0xf bank_mask:0xf
	v_min_f32_dpp v186, v186, v186 row_ror:2 row_mask:0xf bank_mask:0xf
	v_max_f32_dpp v185, v185, v185 row_ror:2 row_mask:0xf bank_mask:0xf
	v_min_f32_dpp v184, v184, v184 row_ror:2 row_mask:0xf bank_mask:0xf
	v_max_f32_dpp v183, v183, v183 row_ror:2 row_mask:0xf bank_mask:0xf
	v_min_f32_dpp v123, v123, v123 row_ror:2 row_mask:0xf bank_mask:0xf
	v_max_f32_dpp v189, v189, v189 row_ror:1 row_mask:0xf bank_mask:0xf
	v_min_f32_dpp v188, v188, v188 row_ror:1 row_mask:0xf bank_mask:0xf
	v_max_f32_dpp v187, v187, v187 row_ror:1 row_mask:0xf bank_mask:0xf
	v_min_f32_dpp v186, v186, v186 row_ror:1 row_mask:0xf bank_mask:0xf
	v_max_f32_dpp v185, v185, v185 row_ror:1 row_mask:0xf bank_mask:0xf
	v_min_f32_dpp v184, v184, v184 row_ror:1 row_mask:0xf bank_mask:0xf
	v_max_f32_dpp v183, v183, v183 row_ror:1 row_mask:0xf bank_mask:0xf
	v_min_f32_dpp v123, v123, v123 row_ror:1 row_mask:0xf bank_mask:0xf
	v_max_f32_dpp v2, v189, v189 row_bcast:15 row_mask:0xa bank_mask:0xf
	v_min_f32_dpp v3, v188, v188 row_bcast:15 row_mask:0xa bank_mask:0xf
	v_max_f32_dpp v4, v187, v187 row_bcast:15 row_mask:0xa bank_mask:0xf
	v_min_f32_dpp v5, v186, v186 row_bcast:15 row_mask:0xa bank_mask:0xf
	v_max_f32_dpp v6, v185, v185 row_bcast:15 row_mask:0xa bank_mask:0xf
	v_min_f32_dpp v7, v184, v184 row_bcast:15 row_mask:0xa bank_mask:0xf
	v_max_f32_dpp v8, v183, v183 row_bcast:15 row_mask:0xa bank_mask:0xf
	v_min_f32_dpp v9, v123, v123 row_bcast:15 row_mask:0xa bank_mask:0xf
	v_cmp_eq_u32_e32 vcc, 16, v110
	s_and_saveexec_b64 s[24:25], vcc
	s_cbranch_execz .LBB0_882
	v_add_u32_e32 v1, 0x26000, v160
	ds_write_b64 v1, v[2:3]
	ds_write_b64 v1, v[4:5] offset:8
	ds_write_b64 v1, v[6:7] offset:32
	ds_write_b64 v1, v[8:9] offset:40
